# GEMM tiles: K-step 1/2 LDS-DMA issued in the tile prologue behind the A0/B0 pieces (prologue wait vmcnt(12))
# speedup vs baseline: 1.0316x; 1.0012x over previous
.LBB0_111:
	v_mov_b64_e32 v[0:1], v[132:133]
	v_mov_b64_e32 v[2:3], v[132:133]
	v_mov_b32_e32 v6, v154
	s_lshl_b32 s46, s13, 8
	s_mov_b64 s[4:5], 0x11a00000
	v_ashrrev_i32_e32 v9, 3, v6
	v_add_u32_e32 v4, s46, v9
	v_lshl_add_u64 v[0:1], v[0:1], 0, s[4:5]
	v_lshrrev_b32_e32 v8, 4, v6
	v_ashrrev_i32_e32 v5, 31, v4
	v_xor_b32_e32 v10, v8, v6
	v_lshlrev_b64 v[4:5], 11, v[4:5]
	v_lshl_add_u64 v[0:1], v[0:1], 0, v[4:5]
	v_lshlrev_b32_e32 v4, 4, v10
	s_lshl_b32 s6, s39, 8
	v_and_b32_e32 v134, 0x70, v4
	v_lshl_add_u64 v[128:129], v[0:1], 0, v[134:135]
	v_add_u32_e32 v0, s6, v9
	v_ashrrev_i32_e32 v1, 31, v0
	v_lshlrev_b64 v[0:1], 11, v[0:1]
	v_ashrrev_i32_e32 v7, 6, v6
	v_lshl_add_u64 v[0:1], v[2:3], 0, v[0:1]
	v_lshl_add_u64 v[130:131], v[0:1], 0, v[134:135]
	v_ashrrev_i32_e32 v0, 1, v6
	v_and_b32_e32 v134, 0xffffffc0, v0
	v_lshlrev_b32_e32 v0, 7, v7
	v_and_b32_e32 v144, 0x80, v0
	v_lshlrev_b32_e32 v0, 10, v7
	v_add_u32_e32 v145, 0, v0
	v_add_u32_e32 v146, s79, v0
	v_readfirstlane_b32 s4, v145
	s_mov_b32 m0, s4
	v_readfirstlane_b32 s4, v146
	v_add_u32_e32 v147, 0x2000, v145
	global_load_lds_dwordx4 v[128:129], off
	s_mov_b32 m0, s4
	s_mov_b64 s[16:17], 0x20000
	v_readfirstlane_b32 s4, v147
	v_add_u32_e32 v148, 0x2000, v146
	global_load_lds_dwordx4 v[130:131], off
	v_lshl_add_u64 v[0:1], v[128:129], 0, s[16:17]
	s_mov_b32 m0, s4
	v_readfirstlane_b32 s4, v148
	v_add_u32_e32 v149, 0x4000, v145
	global_load_lds_dwordx4 v[0:1], off
	v_lshl_add_u64 v[0:1], v[130:131], 0, s[16:17]
	s_mov_b32 m0, s4
	s_mov_b64 s[16:17], 0x40000
	v_readfirstlane_b32 s4, v149
	v_add_u32_e32 v150, 0x4000, v146
	global_load_lds_dwordx4 v[0:1], off
	v_lshl_add_u64 v[0:1], v[128:129], 0, s[16:17]
	s_mov_b32 m0, s4
	v_readfirstlane_b32 s4, v150
	v_add_u32_e32 v151, 0x6000, v145
	global_load_lds_dwordx4 v[0:1], off
	v_lshl_add_u64 v[0:1], v[130:131], 0, s[16:17]
	s_mov_b32 m0, s4
	s_mov_b64 s[16:17], 0x60000
	v_readfirstlane_b32 s4, v151
	v_add_u32_e32 v152, 0x6000, v146
	global_load_lds_dwordx4 v[0:1], off
	v_lshl_add_u64 v[0:1], v[128:129], 0, s[16:17]
	s_mov_b32 m0, s4
	v_readfirstlane_b32 s4, v152
	global_load_lds_dwordx4 v[0:1], off
	v_lshl_add_u64 v[0:1], v[130:131], 0, s[16:17]
	s_mov_b32 m0, s4
	v_and_b32_e32 v143, 15, v6
	global_load_lds_dwordx4 v[0:1], off
	s_mov_b64 s[100:101], 0x80
	v_lshl_add_u64 v[240:241], v[128:129], 0, s[100:101]
	s_mov_b64 s[100:101], 0x20080
	v_lshl_add_u64 v[242:243], v[128:129], 0, s[100:101]
	s_mov_b64 s[100:101], 0x40080
	v_lshl_add_u64 v[244:245], v[128:129], 0, s[100:101]
	s_mov_b64 s[100:101], 0x60080
	v_lshl_add_u64 v[246:247], v[128:129], 0, s[100:101]
	s_mov_b64 s[100:101], 0x80
	v_lshl_add_u64 v[138:139], v[130:131], 0, s[100:101]
	s_mov_b64 s[100:101], 0x20080
	v_lshl_add_u64 v[140:141], v[130:131], 0, s[100:101]
	s_mov_b64 s[100:101], 0x40080
	v_lshl_add_u64 v[250:251], v[130:131], 0, s[100:101]
	s_mov_b64 s[100:101], 0x60080
	v_lshl_add_u64 v[252:253], v[130:131], 0, s[100:101]
	v_readfirstlane_b32 s100, v145
	v_readfirstlane_b32 s101, v146
	s_nop 3
	s_add_u32 m0, s100, 0x8000
	s_nop 0
	global_load_lds_dwordx4 v[240:241], off
	v_lshl_add_u64 v[240:241], v[240:241], 0, s[34:35]
	s_add_u32 m0, s100, 0xa000
	s_nop 0
	global_load_lds_dwordx4 v[242:243], off
	v_lshl_add_u64 v[242:243], v[242:243], 0, s[34:35]
	s_add_u32 m0, s100, 0xc000
	s_nop 0
	global_load_lds_dwordx4 v[244:245], off
	v_lshl_add_u64 v[244:245], v[244:245], 0, s[34:35]
	s_add_u32 m0, s100, 0xe000
	s_nop 0
	global_load_lds_dwordx4 v[246:247], off
	v_lshl_add_u64 v[246:247], v[246:247], 0, s[34:35]
	s_add_u32 m0, s101, 0x8000
	s_nop 0
	global_load_lds_dwordx4 v[138:139], off
	v_lshl_add_u64 v[138:139], v[138:139], 0, s[34:35]
	s_add_u32 m0, s101, 0xa000
	s_nop 0
	global_load_lds_dwordx4 v[140:141], off
	v_lshl_add_u64 v[140:141], v[140:141], 0, s[34:35]
	s_add_u32 m0, s101, 0xc000
	s_nop 0
	global_load_lds_dwordx4 v[250:251], off
	v_lshl_add_u64 v[250:251], v[250:251], 0, s[34:35]
	s_add_u32 m0, s101, 0xe000
	s_nop 0
	global_load_lds_dwordx4 v[252:253], off
	v_lshl_add_u64 v[252:253], v[252:253], 0, s[34:35]
	s_add_u32 m0, s100, 0x20000
	s_nop 0
	global_load_lds_dwordx4 v[240:241], off
	v_lshl_add_u64 v[240:241], v[240:241], 0, s[34:35]
	s_add_u32 m0, s100, 0x22000
	s_nop 0
	global_load_lds_dwordx4 v[242:243], off
	v_lshl_add_u64 v[242:243], v[242:243], 0, s[34:35]
	s_add_u32 m0, s100, 0x24000
	s_nop 0
	global_load_lds_dwordx4 v[244:245], off
	v_lshl_add_u64 v[244:245], v[244:245], 0, s[34:35]
	s_add_u32 m0, s100, 0x26000
	s_nop 0
	global_load_lds_dwordx4 v[246:247], off
	v_lshl_add_u64 v[246:247], v[246:247], 0, s[34:35]
	v_bfe_u32 v142, v6, 4, 2
	v_bfe_u32 v0, v6, 1, 3
	s_waitcnt vmcnt(12)
	v_or_b32_e32 v2, v134, v143
	v_or_b32_e32 v3, v144, v143
	v_bitop3_b32 v1, v8, v0, 3 bitop3:0x6c
	v_bitop3_b32 v0, v142, v0, 4 bitop3:0x36
	v_mov_b32_e32 v4, 0
	v_lshl_add_u32 v153, v2, 7, 0
	v_lshl_add_u32 v169, v3, 7, s79
	v_lshlrev_b32_e32 v170, 4, v1
	v_lshlrev_b32_e32 v171, 4, v0
	s_mov_b64 s[4:5], 0
	v_mov_b32_e32 v5, v4
	v_mov_b32_e32 v6, v4
	v_mov_b32_e32 v7, v4
	v_mov_b32_e32 v12, v4
	v_mov_b32_e32 v13, v4
	v_mov_b32_e32 v14, v4
	v_mov_b32_e32 v15, v4
	v_mov_b32_e32 v0, v4
	v_mov_b32_e32 v1, v4
	v_mov_b32_e32 v2, v4
	v_mov_b32_e32 v3, v4
	v_mov_b32_e32 v8, v4
	v_mov_b32_e32 v9, v4
	v_mov_b32_e32 v10, v4
	v_mov_b32_e32 v11, v4
	v_mov_b32_e32 v20, v4
	v_mov_b32_e32 v21, v4
	v_mov_b32_e32 v22, v4
	v_mov_b32_e32 v23, v4
	v_mov_b32_e32 v28, v4
	v_mov_b32_e32 v29, v4
	v_mov_b32_e32 v30, v4
	v_mov_b32_e32 v31, v4
	v_mov_b32_e32 v16, v4
	v_mov_b32_e32 v17, v4
	v_mov_b32_e32 v18, v4
	v_mov_b32_e32 v19, v4
	v_mov_b32_e32 v24, v4
	v_mov_b32_e32 v25, v4
	v_mov_b32_e32 v26, v4
	v_mov_b32_e32 v27, v4
	v_mov_b32_e32 v36, v4
	v_mov_b32_e32 v37, v4
	v_mov_b32_e32 v38, v4
	v_mov_b32_e32 v39, v4
	v_mov_b32_e32 v44, v4
	v_mov_b32_e32 v45, v4
	v_mov_b32_e32 v46, v4
	v_mov_b32_e32 v47, v4
	v_mov_b32_e32 v32, v4
	v_mov_b32_e32 v33, v4
	v_mov_b32_e32 v34, v4
	v_mov_b32_e32 v35, v4
	v_mov_b32_e32 v40, v4
	v_mov_b32_e32 v41, v4
	v_mov_b32_e32 v42, v4
	v_mov_b32_e32 v43, v4
	v_mov_b32_e32 v52, v4
	v_mov_b32_e32 v53, v4
	v_mov_b32_e32 v54, v4
	v_mov_b32_e32 v55, v4
	v_mov_b32_e32 v60, v4
	v_mov_b32_e32 v61, v4
	v_mov_b32_e32 v62, v4
	v_mov_b32_e32 v63, v4
	v_mov_b32_e32 v48, v4
	v_mov_b32_e32 v49, v4
	v_mov_b32_e32 v50, v4
	v_mov_b32_e32 v51, v4
	v_mov_b32_e32 v56, v4
	v_mov_b32_e32 v57, v4
	v_mov_b32_e32 v58, v4
	v_mov_b32_e32 v59, v4
	v_mov_b32_e32 v68, v4
	v_mov_b32_e32 v69, v4
	v_mov_b32_e32 v70, v4
	v_mov_b32_e32 v71, v4
	v_mov_b32_e32 v76, v4
	v_mov_b32_e32 v77, v4
	v_mov_b32_e32 v78, v4
	v_mov_b32_e32 v79, v4
	v_mov_b32_e32 v64, v4
	v_mov_b32_e32 v65, v4
	v_mov_b32_e32 v66, v4
	v_mov_b32_e32 v67, v4
	v_mov_b32_e32 v72, v4
	v_mov_b32_e32 v73, v4
	v_mov_b32_e32 v74, v4
	v_mov_b32_e32 v75, v4
	v_mov_b32_e32 v84, v4
	v_mov_b32_e32 v85, v4
	v_mov_b32_e32 v86, v4
	v_mov_b32_e32 v87, v4
	v_mov_b32_e32 v92, v4
	v_mov_b32_e32 v93, v4
	v_mov_b32_e32 v94, v4
	v_mov_b32_e32 v95, v4
	v_mov_b32_e32 v80, v4
	v_mov_b32_e32 v81, v4
	v_mov_b32_e32 v82, v4
	v_mov_b32_e32 v83, v4
	v_mov_b32_e32 v88, v4
	v_mov_b32_e32 v89, v4
	v_mov_b32_e32 v90, v4
	v_mov_b32_e32 v91, v4
	v_mov_b32_e32 v100, v4
	v_mov_b32_e32 v101, v4
	v_mov_b32_e32 v102, v4
	v_mov_b32_e32 v103, v4
	v_mov_b32_e32 v108, v4
	v_mov_b32_e32 v109, v4
	v_mov_b32_e32 v110, v4
	v_mov_b32_e32 v111, v4
	v_mov_b32_e32 v96, v4
	v_mov_b32_e32 v97, v4
	v_mov_b32_e32 v98, v4
	v_mov_b32_e32 v99, v4
	v_mov_b32_e32 v104, v4
	v_mov_b32_e32 v105, v4
	v_mov_b32_e32 v106, v4
	v_mov_b32_e32 v107, v4
	v_mov_b32_e32 v116, v4
	v_mov_b32_e32 v117, v4
	v_mov_b32_e32 v118, v4
	v_mov_b32_e32 v119, v4
	v_mov_b32_e32 v124, v4
	v_mov_b32_e32 v125, v4
	v_mov_b32_e32 v126, v4
	v_mov_b32_e32 v127, v4
	v_mov_b32_e32 v112, v4
	v_mov_b32_e32 v113, v4
	v_mov_b32_e32 v114, v4
	v_mov_b32_e32 v115, v4
	v_mov_b32_e32 v120, v4
	v_mov_b32_e32 v121, v4
	v_mov_b32_e32 v122, v4
	v_mov_b32_e32 v123, v4
	s_waitcnt vmcnt(12) lgkmcnt(0)
	s_barrier
	s_branch .LBB0_113
.LBB0_113:
	v_add_u32_e32 v172, v153, v170
	v_add_u32_e32 v173, v153, v171
	v_add_u32_e32 v174, v169, v170
	v_add_u32_e32 v175, v169, v171
	v_add_u32_e32 v254, 0x20000, v172
	v_add_u32_e32 v255, 0x20000, v173
	s_nop 1
	ds_read_b128 v[176:179], v172 offset:0
	ds_read_b128 v[180:183], v172 offset:2048
	ds_read_b128 v[184:187], v172 offset:4096
	ds_read_b128 v[188:191], v172 offset:6144
	ds_read_b128 v[208:211], v174 offset:0
	ds_read_b128 v[212:215], v174 offset:2048
	ds_read_b128 v[216:219], v174 offset:4096
	ds_read_b128 v[220:223], v174 offset:6144
	s_waitcnt lgkmcnt(0)
	v_mfma_f32_16x16x32_bf16 v[120:123], v[208:211], v[176:179], v[120:123]
	ds_read_b128 v[224:227], v174 offset:8192
	v_mfma_f32_16x16x32_bf16 v[112:115], v[212:215], v[176:179], v[112:115]
	ds_read_b128 v[228:231], v174 offset:10240
	v_mfma_f32_16x16x32_bf16 v[124:127], v[216:219], v[176:179], v[124:127]
	ds_read_b128 v[232:235], v174 offset:12288
	v_mfma_f32_16x16x32_bf16 v[116:119], v[220:223], v[176:179], v[116:119]
	ds_read_b128 v[236:239], v174 offset:14336
	v_mfma_f32_16x16x32_bf16 v[88:91], v[208:211], v[180:183], v[88:91]
	v_mfma_f32_16x16x32_bf16 v[80:83], v[212:215], v[180:183], v[80:83]
	v_mfma_f32_16x16x32_bf16 v[92:95], v[216:219], v[180:183], v[92:95]
	v_mfma_f32_16x16x32_bf16 v[84:87], v[220:223], v[180:183], v[84:87]
	v_mfma_f32_16x16x32_bf16 v[56:59], v[208:211], v[184:187], v[56:59]
	v_mfma_f32_16x16x32_bf16 v[48:51], v[212:215], v[184:187], v[48:51]
	v_mfma_f32_16x16x32_bf16 v[60:63], v[216:219], v[184:187], v[60:63]
	v_mfma_f32_16x16x32_bf16 v[52:55], v[220:223], v[184:187], v[52:55]
	v_mfma_f32_16x16x32_bf16 v[24:27], v[208:211], v[188:191], v[24:27]
	v_mfma_f32_16x16x32_bf16 v[16:19], v[212:215], v[188:191], v[16:19]
	v_mfma_f32_16x16x32_bf16 v[28:31], v[216:219], v[188:191], v[28:31]
	v_mfma_f32_16x16x32_bf16 v[20:23], v[220:223], v[188:191], v[20:23]
	s_waitcnt lgkmcnt(0)
	v_mfma_f32_16x16x32_bf16 v[104:107], v[224:227], v[176:179], v[104:107]
	ds_read_b128 v[192:195], v173 offset:0
	v_mfma_f32_16x16x32_bf16 v[96:99], v[228:231], v[176:179], v[96:99]
	ds_read_b128 v[196:199], v173 offset:2048
	v_mfma_f32_16x16x32_bf16 v[108:111], v[232:235], v[176:179], v[108:111]
	ds_read_b128 v[200:203], v173 offset:4096
	v_mfma_f32_16x16x32_bf16 v[100:103], v[236:239], v[176:179], v[100:103]
	ds_read_b128 v[204:207], v173 offset:6144
	v_mfma_f32_16x16x32_bf16 v[72:75], v[224:227], v[180:183], v[72:75]
	ds_read_b128 v[208:211], v175 offset:0
	v_mfma_f32_16x16x32_bf16 v[64:67], v[228:231], v[180:183], v[64:67]
	ds_read_b128 v[212:215], v175 offset:2048
	v_mfma_f32_16x16x32_bf16 v[76:79], v[232:235], v[180:183], v[76:79]
	ds_read_b128 v[216:219], v175 offset:4096
	v_mfma_f32_16x16x32_bf16 v[68:71], v[236:239], v[180:183], v[68:71]
	ds_read_b128 v[220:223], v175 offset:6144
	v_mfma_f32_16x16x32_bf16 v[40:43], v[224:227], v[184:187], v[40:43]
	v_mfma_f32_16x16x32_bf16 v[32:35], v[228:231], v[184:187], v[32:35]
	v_mfma_f32_16x16x32_bf16 v[44:47], v[232:235], v[184:187], v[44:47]
	v_mfma_f32_16x16x32_bf16 v[36:39], v[236:239], v[184:187], v[36:39]
	v_mfma_f32_16x16x32_bf16 v[8:11], v[224:227], v[188:191], v[8:11]
	v_mfma_f32_16x16x32_bf16 v[0:3], v[228:231], v[188:191], v[0:3]
	v_mfma_f32_16x16x32_bf16 v[12:15], v[232:235], v[188:191], v[12:15]
	v_mfma_f32_16x16x32_bf16 v[4:7], v[236:239], v[188:191], v[4:7]
	s_waitcnt lgkmcnt(0)
	v_mfma_f32_16x16x32_bf16 v[120:123], v[208:211], v[192:195], v[120:123]
	ds_read_b128 v[224:227], v175 offset:8192
	v_mfma_f32_16x16x32_bf16 v[112:115], v[212:215], v[192:195], v[112:115]
	ds_read_b128 v[228:231], v175 offset:10240
	v_mfma_f32_16x16x32_bf16 v[124:127], v[216:219], v[192:195], v[124:127]
	ds_read_b128 v[232:235], v175 offset:12288
	v_mfma_f32_16x16x32_bf16 v[116:119], v[220:223], v[192:195], v[116:119]
	ds_read_b128 v[236:239], v175 offset:14336
	v_mfma_f32_16x16x32_bf16 v[88:91], v[208:211], v[196:199], v[88:91]
	v_mfma_f32_16x16x32_bf16 v[80:83], v[212:215], v[196:199], v[80:83]
	v_mfma_f32_16x16x32_bf16 v[92:95], v[216:219], v[196:199], v[92:95]
	v_mfma_f32_16x16x32_bf16 v[84:87], v[220:223], v[196:199], v[84:87]
	v_mfma_f32_16x16x32_bf16 v[56:59], v[208:211], v[200:203], v[56:59]
	v_mfma_f32_16x16x32_bf16 v[48:51], v[212:215], v[200:203], v[48:51]
	v_mfma_f32_16x16x32_bf16 v[60:63], v[216:219], v[200:203], v[60:63]
	v_mfma_f32_16x16x32_bf16 v[52:55], v[220:223], v[200:203], v[52:55]
	v_mfma_f32_16x16x32_bf16 v[24:27], v[208:211], v[204:207], v[24:27]
	v_mfma_f32_16x16x32_bf16 v[16:19], v[212:215], v[204:207], v[16:19]
	v_mfma_f32_16x16x32_bf16 v[28:31], v[216:219], v[204:207], v[28:31]
	v_mfma_f32_16x16x32_bf16 v[20:23], v[220:223], v[204:207], v[20:23]
	s_waitcnt lgkmcnt(0)
	s_waitcnt vmcnt(4)
	s_barrier
	s_mov_b32 s7, 2

.LBB0_1104:
	v_mov_b64_e32 v[0:1], v[132:133]
	v_mov_b64_e32 v[2:3], v[132:133]
	v_mov_b32_e32 v4, v154
	s_lshl_b32 s6, s93, 8
	v_lshrrev_b32_e32 v6, 4, v4
	v_lshl_add_u64 v[0:1], v[0:1], 0, s[22:23]
	v_ashrrev_i32_e32 v7, 3, v4
	v_xor_b32_e32 v8, v6, v4
	v_add_u32_e32 v9, s6, v7
	v_lshlrev_b32_e32 v8, 4, v8
	s_lshl_b32 s7, s89, 8
	v_mad_i64_i32 v[0:1], s[4:5], v9, s50, v[0:1]
	v_and_b32_e32 v134, 0x70, v8
	v_lshl_add_u64 v[128:129], v[0:1], 0, v[134:135]
	v_add_u32_e32 v0, s7, v7
	v_ashrrev_i32_e32 v1, 31, v0
	v_lshl_add_u64 v[2:3], v[2:3], 0, s[16:17]
	v_lshlrev_b64 v[0:1], 11, v[0:1]
	v_ashrrev_i32_e32 v5, 6, v4
	v_lshl_add_u64 v[0:1], v[2:3], 0, v[0:1]
	v_lshl_add_u64 v[130:131], v[0:1], 0, v[134:135]
	v_ashrrev_i32_e32 v0, 1, v4
	v_and_b32_e32 v134, 0xffffffc0, v0
	v_lshlrev_b32_e32 v0, 7, v5
	v_and_b32_e32 v143, 0x80, v0
	v_lshlrev_b32_e32 v0, 10, v5
	v_add_u32_e32 v144, 0, v0
	v_add_u32_e32 v145, s79, v0
	v_readfirstlane_b32 s4, v144
	s_mov_b32 m0, s4
	v_readfirstlane_b32 s4, v145
	global_load_lds_dwordx4 v[128:129], off
	s_mov_b32 m0, s4
	s_mov_b64 s[4:5], 0x6c000
	v_add_u32_e32 v146, 0x2000, v144
	v_lshl_add_u64 v[0:1], v[128:129], 0, s[4:5]
	v_readfirstlane_b32 s4, v146
	global_load_lds_dwordx4 v[130:131], off
	s_mov_b32 m0, s4
	s_mov_b64 s[4:5], 0x20000
	v_add_u32_e32 v147, 0x2000, v145
	global_load_lds_dwordx4 v[0:1], off
	v_lshl_add_u64 v[0:1], v[130:131], 0, s[4:5]
	v_readfirstlane_b32 s4, v147
	s_mov_b32 m0, s4
	s_mov_b64 s[4:5], 0xd8000
	v_add_u32_e32 v148, 0x4000, v144
	global_load_lds_dwordx4 v[0:1], off
	v_lshl_add_u64 v[0:1], v[128:129], 0, s[4:5]
	v_readfirstlane_b32 s4, v148
	s_mov_b32 m0, s4
	s_mov_b64 s[4:5], 0x40000
	v_add_u32_e32 v149, 0x4000, v145
	global_load_lds_dwordx4 v[0:1], off
	v_lshl_add_u64 v[0:1], v[130:131], 0, s[4:5]
	v_readfirstlane_b32 s4, v149
	s_mov_b32 m0, s4
	s_mov_b64 s[4:5], 0x144000
	v_add_u32_e32 v151, 0x6000, v144
	global_load_lds_dwordx4 v[0:1], off
	v_lshl_add_u64 v[0:1], v[128:129], 0, s[4:5]
	v_readfirstlane_b32 s4, v151
	s_mov_b32 m0, s4
	s_mov_b64 s[4:5], 0x60000
	v_add_u32_e32 v152, 0x6000, v145
	global_load_lds_dwordx4 v[0:1], off
	v_lshl_add_u64 v[0:1], v[130:131], 0, s[4:5]
	v_readfirstlane_b32 s4, v152
	s_mov_b32 m0, s4
	v_bfe_u32 v150, v4, 4, 2
	global_load_lds_dwordx4 v[0:1], off
	s_mov_b64 s[100:101], 0x80
	v_lshl_add_u64 v[240:241], v[128:129], 0, s[100:101]
	s_mov_b64 s[100:101], 0x6c080
	v_lshl_add_u64 v[242:243], v[128:129], 0, s[100:101]
	s_mov_b64 s[100:101], 0xd8080
	v_lshl_add_u64 v[244:245], v[128:129], 0, s[100:101]
	s_mov_b64 s[100:101], 0x144080
	v_lshl_add_u64 v[246:247], v[128:129], 0, s[100:101]
	s_mov_b64 s[100:101], 0x80
	v_lshl_add_u64 v[138:139], v[130:131], 0, s[100:101]
	s_mov_b64 s[100:101], 0x20080
	v_lshl_add_u64 v[140:141], v[130:131], 0, s[100:101]
	s_mov_b64 s[100:101], 0x40080
	v_lshl_add_u64 v[250:251], v[130:131], 0, s[100:101]
	s_mov_b64 s[100:101], 0x60080
	v_lshl_add_u64 v[252:253], v[130:131], 0, s[100:101]
	v_readfirstlane_b32 s100, v144
	v_readfirstlane_b32 s101, v145
	s_nop 3
	s_add_u32 m0, s100, 0x8000
	s_nop 0
	global_load_lds_dwordx4 v[240:241], off
	v_lshl_add_u64 v[240:241], v[240:241], 0, s[34:35]
	s_add_u32 m0, s100, 0xa000
	s_nop 0
	global_load_lds_dwordx4 v[242:243], off
	v_lshl_add_u64 v[242:243], v[242:243], 0, s[34:35]
	s_add_u32 m0, s100, 0xc000
	s_nop 0
	global_load_lds_dwordx4 v[244:245], off
	v_lshl_add_u64 v[244:245], v[244:245], 0, s[34:35]
	s_add_u32 m0, s100, 0xe000
	s_nop 0
	global_load_lds_dwordx4 v[246:247], off
	v_lshl_add_u64 v[246:247], v[246:247], 0, s[34:35]
	s_add_u32 m0, s101, 0x8000
	s_nop 0
	global_load_lds_dwordx4 v[138:139], off
	v_lshl_add_u64 v[138:139], v[138:139], 0, s[34:35]
	s_add_u32 m0, s101, 0xa000
	s_nop 0
	global_load_lds_dwordx4 v[140:141], off
	v_lshl_add_u64 v[140:141], v[140:141], 0, s[34:35]
	s_add_u32 m0, s101, 0xc000
	s_nop 0
	global_load_lds_dwordx4 v[250:251], off
	v_lshl_add_u64 v[250:251], v[250:251], 0, s[34:35]
	s_add_u32 m0, s101, 0xe000
	s_nop 0
	global_load_lds_dwordx4 v[252:253], off
	v_lshl_add_u64 v[252:253], v[252:253], 0, s[34:35]
	s_add_u32 m0, s100, 0x20000
	s_nop 0
	global_load_lds_dwordx4 v[240:241], off
	v_lshl_add_u64 v[240:241], v[240:241], 0, s[34:35]
	s_add_u32 m0, s100, 0x22000
	s_nop 0
	global_load_lds_dwordx4 v[242:243], off
	v_lshl_add_u64 v[242:243], v[242:243], 0, s[34:35]
	s_add_u32 m0, s100, 0x24000
	s_nop 0
	global_load_lds_dwordx4 v[244:245], off
	v_lshl_add_u64 v[244:245], v[244:245], 0, s[34:35]
	s_add_u32 m0, s100, 0x26000
	s_nop 0
	global_load_lds_dwordx4 v[246:247], off
	v_lshl_add_u64 v[246:247], v[246:247], 0, s[34:35]
	v_bfe_u32 v0, v4, 1, 3
	v_and_b32_e32 v142, 15, v4
	s_waitcnt vmcnt(12)
	v_bitop3_b32 v1, v6, v0, 3 bitop3:0x6c
	v_bitop3_b32 v0, v150, v0, 4 bitop3:0x36
	v_or_b32_e32 v2, v134, v142
	v_or_b32_e32 v3, v143, v142
	v_lshlrev_b32_e32 v171, 4, v0
	v_mov_b32_e32 v0, 0
	v_lshl_add_u32 v153, v2, 7, 0
	v_lshl_add_u32 v169, v3, 7, s79
	v_lshlrev_b32_e32 v170, 4, v1
	s_mov_b64 s[4:5], 0
	v_mov_b32_e32 v1, v0
	v_mov_b32_e32 v2, v0
	v_mov_b32_e32 v3, v0
	v_mov_b32_e32 v4, v0
	v_mov_b32_e32 v5, v0
	v_mov_b32_e32 v6, v0
	v_mov_b32_e32 v7, v0
	v_mov_b32_e32 v8, v0
	v_mov_b32_e32 v9, v0
	v_mov_b32_e32 v10, v0
	v_mov_b32_e32 v11, v0
	v_mov_b32_e32 v12, v0
	v_mov_b32_e32 v13, v0
	v_mov_b32_e32 v14, v0
	v_mov_b32_e32 v15, v0
	v_mov_b32_e32 v16, v0
	v_mov_b32_e32 v17, v0
	v_mov_b32_e32 v18, v0
	v_mov_b32_e32 v19, v0
	v_mov_b32_e32 v20, v0
	v_mov_b32_e32 v21, v0
	v_mov_b32_e32 v22, v0
	v_mov_b32_e32 v23, v0
	v_mov_b32_e32 v24, v0
	v_mov_b32_e32 v25, v0
	v_mov_b32_e32 v26, v0
	v_mov_b32_e32 v27, v0
	v_mov_b32_e32 v28, v0
	v_mov_b32_e32 v29, v0
	v_mov_b32_e32 v30, v0
	v_mov_b32_e32 v31, v0
	v_mov_b32_e32 v32, v0
	v_mov_b32_e32 v33, v0
	v_mov_b32_e32 v34, v0
	v_mov_b32_e32 v35, v0
	v_mov_b32_e32 v36, v0
	v_mov_b32_e32 v37, v0
	v_mov_b32_e32 v38, v0
	v_mov_b32_e32 v39, v0
	v_mov_b32_e32 v40, v0
	v_mov_b32_e32 v41, v0
	v_mov_b32_e32 v42, v0
	v_mov_b32_e32 v43, v0
	v_mov_b32_e32 v44, v0
	v_mov_b32_e32 v45, v0
	v_mov_b32_e32 v46, v0
	v_mov_b32_e32 v47, v0
	v_mov_b32_e32 v48, v0
	v_mov_b32_e32 v49, v0
	v_mov_b32_e32 v50, v0
	v_mov_b32_e32 v51, v0
	v_mov_b32_e32 v52, v0
	v_mov_b32_e32 v53, v0
	v_mov_b32_e32 v54, v0
	v_mov_b32_e32 v55, v0
	v_mov_b32_e32 v56, v0
	v_mov_b32_e32 v57, v0
	v_mov_b32_e32 v58, v0
	v_mov_b32_e32 v59, v0
	v_mov_b32_e32 v60, v0
	v_mov_b32_e32 v61, v0
	v_mov_b32_e32 v62, v0
	v_mov_b32_e32 v63, v0
	v_mov_b32_e32 v64, v0
	v_mov_b32_e32 v65, v0
	v_mov_b32_e32 v66, v0
	v_mov_b32_e32 v67, v0
	v_mov_b32_e32 v68, v0
	v_mov_b32_e32 v69, v0
	v_mov_b32_e32 v70, v0
	v_mov_b32_e32 v71, v0
	v_mov_b32_e32 v72, v0
	v_mov_b32_e32 v73, v0
	s_waitcnt vmcnt(12)
	v_mov_b32_e32 v74, v0
	v_mov_b32_e32 v75, v0
	v_mov_b32_e32 v76, v0
	v_mov_b32_e32 v77, v0
	v_mov_b32_e32 v78, v0
	v_mov_b32_e32 v79, v0
	v_mov_b32_e32 v80, v0
	v_mov_b32_e32 v81, v0
	v_mov_b32_e32 v82, v0
	v_mov_b32_e32 v83, v0
	v_mov_b32_e32 v84, v0
	v_mov_b32_e32 v85, v0
	v_mov_b32_e32 v86, v0
	v_mov_b32_e32 v87, v0
	v_mov_b32_e32 v88, v0
	v_mov_b32_e32 v89, v0
	v_mov_b32_e32 v90, v0
	v_mov_b32_e32 v91, v0
	v_mov_b32_e32 v92, v0
	v_mov_b32_e32 v93, v0
	v_mov_b32_e32 v94, v0
	v_mov_b32_e32 v95, v0
	v_mov_b32_e32 v96, v0
	v_mov_b32_e32 v97, v0
	v_mov_b32_e32 v98, v0
	v_mov_b32_e32 v99, v0
	v_mov_b32_e32 v100, v0
	v_mov_b32_e32 v101, v0
	v_mov_b32_e32 v102, v0
	v_mov_b32_e32 v103, v0
	v_mov_b32_e32 v104, v0
	v_mov_b32_e32 v105, v0
	v_mov_b32_e32 v106, v0
	v_mov_b32_e32 v107, v0
	v_mov_b32_e32 v108, v0
	v_mov_b32_e32 v109, v0
	v_mov_b32_e32 v110, v0
	v_mov_b32_e32 v111, v0
	v_mov_b32_e32 v112, v0
	v_mov_b32_e32 v113, v0
	v_mov_b32_e32 v114, v0
	v_mov_b32_e32 v115, v0
	v_mov_b32_e32 v116, v0
	v_mov_b32_e32 v117, v0
	v_mov_b32_e32 v118, v0
	v_mov_b32_e32 v119, v0
	v_mov_b32_e32 v120, v0
	v_mov_b32_e32 v121, v0
	v_mov_b32_e32 v122, v0
	v_mov_b32_e32 v123, v0
	v_mov_b32_e32 v124, v0
	v_mov_b32_e32 v125, v0
	v_mov_b32_e32 v126, v0
	v_mov_b32_e32 v127, v0
	s_waitcnt lgkmcnt(0)
	s_barrier
	s_branch .LBB0_1106
.LBB0_1106:
	v_add_u32_e32 v172, v153, v170
	v_add_u32_e32 v173, v153, v171
	v_add_u32_e32 v174, v169, v170
	v_add_u32_e32 v175, v169, v171
	v_add_u32_e32 v254, 0x20000, v172
	v_add_u32_e32 v255, 0x20000, v173
	s_nop 1
	ds_read_b128 v[176:179], v172 offset:0
	ds_read_b128 v[180:183], v172 offset:2048
	ds_read_b128 v[184:187], v172 offset:4096
	ds_read_b128 v[188:191], v172 offset:6144
	ds_read_b128 v[208:211], v174 offset:0
	ds_read_b128 v[212:215], v174 offset:2048
	ds_read_b128 v[216:219], v174 offset:4096
	ds_read_b128 v[220:223], v174 offset:6144
	s_waitcnt lgkmcnt(0)
	v_mfma_f32_16x16x32_bf16 v[124:127], v[208:211], v[176:179], v[124:127]
	ds_read_b128 v[224:227], v174 offset:8192
	v_mfma_f32_16x16x32_bf16 v[120:123], v[212:215], v[176:179], v[120:123]
	ds_read_b128 v[228:231], v174 offset:10240
	v_mfma_f32_16x16x32_bf16 v[116:119], v[216:219], v[176:179], v[116:119]
	ds_read_b128 v[232:235], v174 offset:12288
	v_mfma_f32_16x16x32_bf16 v[112:115], v[220:223], v[176:179], v[112:115]
	ds_read_b128 v[236:239], v174 offset:14336
	v_mfma_f32_16x16x32_bf16 v[92:95], v[208:211], v[180:183], v[92:95]
	v_mfma_f32_16x16x32_bf16 v[88:91], v[212:215], v[180:183], v[88:91]
	v_mfma_f32_16x16x32_bf16 v[84:87], v[216:219], v[180:183], v[84:87]
	v_mfma_f32_16x16x32_bf16 v[80:83], v[220:223], v[180:183], v[80:83]
	v_mfma_f32_16x16x32_bf16 v[60:63], v[208:211], v[184:187], v[60:63]
	v_mfma_f32_16x16x32_bf16 v[56:59], v[212:215], v[184:187], v[56:59]
	v_mfma_f32_16x16x32_bf16 v[52:55], v[216:219], v[184:187], v[52:55]
	v_mfma_f32_16x16x32_bf16 v[48:51], v[220:223], v[184:187], v[48:51]
	v_mfma_f32_16x16x32_bf16 v[28:31], v[208:211], v[188:191], v[28:31]
	v_mfma_f32_16x16x32_bf16 v[24:27], v[212:215], v[188:191], v[24:27]
	v_mfma_f32_16x16x32_bf16 v[20:23], v[216:219], v[188:191], v[20:23]
	v_mfma_f32_16x16x32_bf16 v[16:19], v[220:223], v[188:191], v[16:19]
	s_waitcnt lgkmcnt(0)
	v_mfma_f32_16x16x32_bf16 v[108:111], v[224:227], v[176:179], v[108:111]
	ds_read_b128 v[192:195], v173 offset:0
	v_mfma_f32_16x16x32_bf16 v[104:107], v[228:231], v[176:179], v[104:107]
	ds_read_b128 v[196:199], v173 offset:2048
	v_mfma_f32_16x16x32_bf16 v[100:103], v[232:235], v[176:179], v[100:103]
	ds_read_b128 v[200:203], v173 offset:4096
	v_mfma_f32_16x16x32_bf16 v[96:99], v[236:239], v[176:179], v[96:99]
	ds_read_b128 v[204:207], v173 offset:6144
	v_mfma_f32_16x16x32_bf16 v[76:79], v[224:227], v[180:183], v[76:79]
	ds_read_b128 v[208:211], v175 offset:0
	v_mfma_f32_16x16x32_bf16 v[72:75], v[228:231], v[180:183], v[72:75]
	ds_read_b128 v[212:215], v175 offset:2048
	v_mfma_f32_16x16x32_bf16 v[68:71], v[232:235], v[180:183], v[68:71]
	ds_read_b128 v[216:219], v175 offset:4096
	v_mfma_f32_16x16x32_bf16 v[64:67], v[236:239], v[180:183], v[64:67]
	ds_read_b128 v[220:223], v175 offset:6144
	v_mfma_f32_16x16x32_bf16 v[44:47], v[224:227], v[184:187], v[44:47]
	v_mfma_f32_16x16x32_bf16 v[40:43], v[228:231], v[184:187], v[40:43]
	v_mfma_f32_16x16x32_bf16 v[36:39], v[232:235], v[184:187], v[36:39]
	v_mfma_f32_16x16x32_bf16 v[32:35], v[236:239], v[184:187], v[32:35]
	v_mfma_f32_16x16x32_bf16 v[12:15], v[224:227], v[188:191], v[12:15]
	v_mfma_f32_16x16x32_bf16 v[8:11], v[228:231], v[188:191], v[8:11]
	v_mfma_f32_16x16x32_bf16 v[4:7], v[232:235], v[188:191], v[4:7]
	v_mfma_f32_16x16x32_bf16 v[0:3], v[236:239], v[188:191], v[0:3]
	s_waitcnt lgkmcnt(0)
	v_mfma_f32_16x16x32_bf16 v[124:127], v[208:211], v[192:195], v[124:127]
	ds_read_b128 v[224:227], v175 offset:8192
	v_mfma_f32_16x16x32_bf16 v[120:123], v[212:215], v[192:195], v[120:123]
	ds_read_b128 v[228:231], v175 offset:10240
	v_mfma_f32_16x16x32_bf16 v[116:119], v[216:219], v[192:195], v[116:119]
	ds_read_b128 v[232:235], v175 offset:12288
	v_mfma_f32_16x16x32_bf16 v[112:115], v[220:223], v[192:195], v[112:115]
	ds_read_b128 v[236:239], v175 offset:14336
	v_mfma_f32_16x16x32_bf16 v[92:95], v[208:211], v[196:199], v[92:95]
	v_mfma_f32_16x16x32_bf16 v[88:91], v[212:215], v[196:199], v[88:91]
	v_mfma_f32_16x16x32_bf16 v[84:87], v[216:219], v[196:199], v[84:87]
	v_mfma_f32_16x16x32_bf16 v[80:83], v[220:223], v[196:199], v[80:83]
	v_mfma_f32_16x16x32_bf16 v[60:63], v[208:211], v[200:203], v[60:63]
	v_mfma_f32_16x16x32_bf16 v[56:59], v[212:215], v[200:203], v[56:59]
	v_mfma_f32_16x16x32_bf16 v[52:55], v[216:219], v[200:203], v[52:55]
	v_mfma_f32_16x16x32_bf16 v[48:51], v[220:223], v[200:203], v[48:51]
	v_mfma_f32_16x16x32_bf16 v[28:31], v[208:211], v[204:207], v[28:31]
	v_mfma_f32_16x16x32_bf16 v[24:27], v[212:215], v[204:207], v[24:27]
	v_mfma_f32_16x16x32_bf16 v[20:23], v[216:219], v[204:207], v[20:23]
	v_mfma_f32_16x16x32_bf16 v[16:19], v[220:223], v[204:207], v[16:19]
	s_waitcnt lgkmcnt(0)
	s_waitcnt vmcnt(4)
	s_barrier
	s_mov_b32 s46, 2

.LBB0_1134:
	v_mov_b64_e32 v[0:1], v[132:133]
	v_mov_b64_e32 v[2:3], v[132:133]
	v_mov_b32_e32 v6, v154
	s_lshl_b32 s6, s88, 8
	s_mov_b64 s[4:5], 0x11a00000
	v_ashrrev_i32_e32 v9, 3, v6
	v_add_u32_e32 v4, s6, v9
	v_lshl_add_u64 v[0:1], v[0:1], 0, s[4:5]
	v_lshrrev_b32_e32 v8, 4, v6
	v_ashrrev_i32_e32 v5, 31, v4
	v_xor_b32_e32 v10, v8, v6
	v_lshlrev_b64 v[4:5], 11, v[4:5]
	v_lshl_add_u64 v[0:1], v[0:1], 0, v[4:5]
	v_lshlrev_b32_e32 v4, 4, v10
	s_lshl_b32 s7, s92, 8
	v_and_b32_e32 v134, 0x70, v4
	v_lshl_add_u64 v[128:129], v[0:1], 0, v[134:135]
	v_add_u32_e32 v0, s7, v9
	s_mov_b64 s[4:5], 0x8c0000
	v_ashrrev_i32_e32 v1, 31, v0
	v_lshl_add_u64 v[2:3], v[2:3], 0, s[4:5]
	v_lshlrev_b64 v[0:1], 11, v[0:1]
	v_ashrrev_i32_e32 v7, 6, v6
	v_lshl_add_u64 v[0:1], v[2:3], 0, v[0:1]
	v_lshl_add_u64 v[130:131], v[0:1], 0, v[134:135]
	v_ashrrev_i32_e32 v0, 1, v6
	v_and_b32_e32 v134, 0xffffffc0, v0
	v_lshlrev_b32_e32 v0, 7, v7
	v_and_b32_e32 v143, 0x80, v0
	v_lshlrev_b32_e32 v0, 10, v7
	v_add_u32_e32 v144, 0, v0
	v_add_u32_e32 v145, s79, v0
	v_readfirstlane_b32 s4, v144
	s_mov_b32 m0, s4
	v_readfirstlane_b32 s4, v145
	v_add_u32_e32 v146, 0x2000, v144
	global_load_lds_dwordx4 v[128:129], off
	s_mov_b32 m0, s4
	s_mov_b64 s[20:21], 0x20000
	v_readfirstlane_b32 s4, v146
	v_add_u32_e32 v147, 0x2000, v145
	global_load_lds_dwordx4 v[130:131], off
	v_lshl_add_u64 v[0:1], v[128:129], 0, s[20:21]
	s_mov_b32 m0, s4
	v_readfirstlane_b32 s4, v147
	v_add_u32_e32 v148, 0x4000, v144
	global_load_lds_dwordx4 v[0:1], off
	v_lshl_add_u64 v[0:1], v[130:131], 0, s[20:21]
	s_mov_b32 m0, s4
	s_mov_b64 s[20:21], 0x40000
	v_readfirstlane_b32 s4, v148
	v_add_u32_e32 v150, 0x4000, v145
	global_load_lds_dwordx4 v[0:1], off
	v_lshl_add_u64 v[0:1], v[128:129], 0, s[20:21]
	s_mov_b32 m0, s4
	v_readfirstlane_b32 s4, v150
	v_add_u32_e32 v151, 0x6000, v144
	global_load_lds_dwordx4 v[0:1], off
	v_lshl_add_u64 v[0:1], v[130:131], 0, s[20:21]
	s_mov_b32 m0, s4
	s_mov_b64 s[20:21], 0x60000
	v_readfirstlane_b32 s4, v151
	v_add_u32_e32 v152, 0x6000, v145
	global_load_lds_dwordx4 v[0:1], off
	v_lshl_add_u64 v[0:1], v[128:129], 0, s[20:21]
	s_mov_b32 m0, s4
	v_readfirstlane_b32 s4, v152
	global_load_lds_dwordx4 v[0:1], off
	v_lshl_add_u64 v[0:1], v[130:131], 0, s[20:21]
	s_mov_b32 m0, s4
	v_bfe_u32 v149, v6, 4, 2
	global_load_lds_dwordx4 v[0:1], off
	s_mov_b64 s[100:101], 0x80
	v_lshl_add_u64 v[240:241], v[128:129], 0, s[100:101]
	s_mov_b64 s[100:101], 0x20080
	v_lshl_add_u64 v[242:243], v[128:129], 0, s[100:101]
	s_mov_b64 s[100:101], 0x40080
	v_lshl_add_u64 v[244:245], v[128:129], 0, s[100:101]
	s_mov_b64 s[100:101], 0x60080
	v_lshl_add_u64 v[246:247], v[128:129], 0, s[100:101]
	s_mov_b64 s[100:101], 0x80
	v_lshl_add_u64 v[138:139], v[130:131], 0, s[100:101]
	s_mov_b64 s[100:101], 0x20080
	v_lshl_add_u64 v[140:141], v[130:131], 0, s[100:101]
	s_mov_b64 s[100:101], 0x40080
	v_lshl_add_u64 v[250:251], v[130:131], 0, s[100:101]
	s_mov_b64 s[100:101], 0x60080
	v_lshl_add_u64 v[252:253], v[130:131], 0, s[100:101]
	v_readfirstlane_b32 s100, v144
	v_readfirstlane_b32 s101, v145
	s_nop 3
	s_add_u32 m0, s100, 0x8000
	s_nop 0
	global_load_lds_dwordx4 v[240:241], off
	v_lshl_add_u64 v[240:241], v[240:241], 0, s[34:35]
	s_add_u32 m0, s100, 0xa000
	s_nop 0
	global_load_lds_dwordx4 v[242:243], off
	v_lshl_add_u64 v[242:243], v[242:243], 0, s[34:35]
	s_add_u32 m0, s100, 0xc000
	s_nop 0
	global_load_lds_dwordx4 v[244:245], off
	v_lshl_add_u64 v[244:245], v[244:245], 0, s[34:35]
	s_add_u32 m0, s100, 0xe000
	s_nop 0
	global_load_lds_dwordx4 v[246:247], off
	v_lshl_add_u64 v[246:247], v[246:247], 0, s[34:35]
	s_add_u32 m0, s101, 0x8000
	s_nop 0
	global_load_lds_dwordx4 v[138:139], off
	v_lshl_add_u64 v[138:139], v[138:139], 0, s[34:35]
	s_add_u32 m0, s101, 0xa000
	s_nop 0
	global_load_lds_dwordx4 v[140:141], off
	v_lshl_add_u64 v[140:141], v[140:141], 0, s[34:35]
	s_add_u32 m0, s101, 0xc000
	s_nop 0
	global_load_lds_dwordx4 v[250:251], off
	v_lshl_add_u64 v[250:251], v[250:251], 0, s[34:35]
	s_add_u32 m0, s101, 0xe000
	s_nop 0
	global_load_lds_dwordx4 v[252:253], off
	v_lshl_add_u64 v[252:253], v[252:253], 0, s[34:35]
	s_add_u32 m0, s100, 0x20000
	s_nop 0
	global_load_lds_dwordx4 v[240:241], off
	v_lshl_add_u64 v[240:241], v[240:241], 0, s[34:35]
	s_add_u32 m0, s100, 0x22000
	s_nop 0
	global_load_lds_dwordx4 v[242:243], off
	v_lshl_add_u64 v[242:243], v[242:243], 0, s[34:35]
	s_add_u32 m0, s100, 0x24000
	s_nop 0
	global_load_lds_dwordx4 v[244:245], off
	v_lshl_add_u64 v[244:245], v[244:245], 0, s[34:35]
	s_add_u32 m0, s100, 0x26000
	s_nop 0
	global_load_lds_dwordx4 v[246:247], off
	v_lshl_add_u64 v[246:247], v[246:247], 0, s[34:35]
	v_bfe_u32 v0, v6, 1, 3
	v_and_b32_e32 v142, 15, v6
	s_waitcnt vmcnt(12)
	v_bitop3_b32 v1, v8, v0, 3 bitop3:0x6c
	v_bitop3_b32 v0, v149, v0, 4 bitop3:0x36
	v_or_b32_e32 v2, v134, v142
	v_or_b32_e32 v3, v143, v142
	v_lshlrev_b32_e32 v171, 4, v0
	v_mov_b32_e32 v0, 0
	v_lshl_add_u32 v153, v2, 7, 0
	v_lshl_add_u32 v169, v3, 7, s79
	v_lshlrev_b32_e32 v170, 4, v1
	s_mov_b64 s[4:5], 0
	v_mov_b32_e32 v1, v0
	v_mov_b32_e32 v2, v0
	v_mov_b32_e32 v3, v0
	v_mov_b32_e32 v4, v0
	v_mov_b32_e32 v5, v0
	v_mov_b32_e32 v6, v0
	v_mov_b32_e32 v7, v0
	v_mov_b32_e32 v8, v0
	v_mov_b32_e32 v9, v0
	v_mov_b32_e32 v10, v0
	v_mov_b32_e32 v11, v0
	v_mov_b32_e32 v12, v0
	v_mov_b32_e32 v13, v0
	v_mov_b32_e32 v14, v0
	v_mov_b32_e32 v15, v0
	v_mov_b32_e32 v16, v0
	v_mov_b32_e32 v17, v0
	v_mov_b32_e32 v18, v0
	v_mov_b32_e32 v19, v0
	v_mov_b32_e32 v20, v0
	v_mov_b32_e32 v21, v0
	v_mov_b32_e32 v22, v0
	v_mov_b32_e32 v23, v0
	v_mov_b32_e32 v24, v0
	v_mov_b32_e32 v25, v0
	v_mov_b32_e32 v26, v0
	v_mov_b32_e32 v27, v0
	v_mov_b32_e32 v28, v0
	v_mov_b32_e32 v29, v0
	v_mov_b32_e32 v30, v0
	v_mov_b32_e32 v31, v0
	v_mov_b32_e32 v32, v0
	v_mov_b32_e32 v33, v0
	v_mov_b32_e32 v34, v0
	v_mov_b32_e32 v35, v0
	v_mov_b32_e32 v36, v0
	v_mov_b32_e32 v37, v0
	v_mov_b32_e32 v38, v0
	v_mov_b32_e32 v39, v0
	v_mov_b32_e32 v40, v0
	v_mov_b32_e32 v41, v0
	v_mov_b32_e32 v42, v0
	v_mov_b32_e32 v43, v0
	v_mov_b32_e32 v44, v0
	v_mov_b32_e32 v45, v0
	v_mov_b32_e32 v46, v0
	v_mov_b32_e32 v47, v0
	v_mov_b32_e32 v48, v0
	v_mov_b32_e32 v49, v0
	v_mov_b32_e32 v50, v0
	v_mov_b32_e32 v51, v0
	v_mov_b32_e32 v52, v0
	v_mov_b32_e32 v53, v0
	v_mov_b32_e32 v54, v0
	v_mov_b32_e32 v55, v0
	v_mov_b32_e32 v56, v0
	v_mov_b32_e32 v57, v0
	v_mov_b32_e32 v58, v0
	v_mov_b32_e32 v59, v0
	v_mov_b32_e32 v60, v0
	v_mov_b32_e32 v61, v0
	v_mov_b32_e32 v62, v0
	v_mov_b32_e32 v63, v0
	v_mov_b32_e32 v64, v0
	v_mov_b32_e32 v65, v0
	v_mov_b32_e32 v66, v0
	v_mov_b32_e32 v67, v0
	v_mov_b32_e32 v68, v0
	v_mov_b32_e32 v69, v0
	v_mov_b32_e32 v70, v0
	v_mov_b32_e32 v71, v0
	v_mov_b32_e32 v72, v0
	v_mov_b32_e32 v73, v0
	v_mov_b32_e32 v74, v0
	v_mov_b32_e32 v75, v0
	v_mov_b32_e32 v76, v0
	v_mov_b32_e32 v77, v0
	v_mov_b32_e32 v78, v0
	v_mov_b32_e32 v79, v0
	v_mov_b32_e32 v80, v0
	v_mov_b32_e32 v81, v0
	v_mov_b32_e32 v82, v0
	v_mov_b32_e32 v83, v0
	v_mov_b32_e32 v84, v0
	v_mov_b32_e32 v85, v0
	v_mov_b32_e32 v86, v0
	v_mov_b32_e32 v87, v0
	v_mov_b32_e32 v88, v0
	v_mov_b32_e32 v89, v0
	v_mov_b32_e32 v90, v0
	v_mov_b32_e32 v91, v0
	v_mov_b32_e32 v92, v0
	v_mov_b32_e32 v93, v0
	v_mov_b32_e32 v94, v0
	v_mov_b32_e32 v95, v0
	v_mov_b32_e32 v96, v0
	v_mov_b32_e32 v97, v0
	v_mov_b32_e32 v98, v0
	v_mov_b32_e32 v99, v0
	v_mov_b32_e32 v100, v0
	v_mov_b32_e32 v101, v0
	v_mov_b32_e32 v102, v0
	v_mov_b32_e32 v103, v0
	v_mov_b32_e32 v104, v0
	v_mov_b32_e32 v105, v0
	v_mov_b32_e32 v106, v0
	v_mov_b32_e32 v107, v0
	v_mov_b32_e32 v108, v0
	v_mov_b32_e32 v109, v0
	v_mov_b32_e32 v110, v0
	v_mov_b32_e32 v111, v0
	v_mov_b32_e32 v112, v0
	v_mov_b32_e32 v113, v0
	v_mov_b32_e32 v114, v0
	v_mov_b32_e32 v115, v0
	v_mov_b32_e32 v116, v0
	v_mov_b32_e32 v117, v0
	v_mov_b32_e32 v118, v0
	v_mov_b32_e32 v119, v0
	v_mov_b32_e32 v120, v0
	v_mov_b32_e32 v121, v0
	v_mov_b32_e32 v122, v0
	v_mov_b32_e32 v123, v0
	v_mov_b32_e32 v124, v0
	v_mov_b32_e32 v125, v0
	v_mov_b32_e32 v126, v0
	v_mov_b32_e32 v127, v0
	s_waitcnt vmcnt(12) lgkmcnt(0)
	s_barrier
	s_branch .LBB0_1136
.LBB0_1136:
	v_add_u32_e32 v172, v153, v170
	v_add_u32_e32 v173, v153, v171
	v_add_u32_e32 v174, v169, v170
	v_add_u32_e32 v175, v169, v171
	v_add_u32_e32 v254, 0x20000, v172
	v_add_u32_e32 v255, 0x20000, v173
	s_nop 1
	ds_read_b128 v[176:179], v172 offset:0
	ds_read_b128 v[180:183], v172 offset:2048
	ds_read_b128 v[184:187], v172 offset:4096
	ds_read_b128 v[188:191], v172 offset:6144
	ds_read_b128 v[208:211], v174 offset:0
	ds_read_b128 v[212:215], v174 offset:2048
	ds_read_b128 v[216:219], v174 offset:4096
	ds_read_b128 v[220:223], v174 offset:6144
	s_waitcnt lgkmcnt(0)
	v_mfma_f32_16x16x32_bf16 v[124:127], v[208:211], v[176:179], v[124:127]
	ds_read_b128 v[224:227], v174 offset:8192
	v_mfma_f32_16x16x32_bf16 v[120:123], v[212:215], v[176:179], v[120:123]
	ds_read_b128 v[228:231], v174 offset:10240
	v_mfma_f32_16x16x32_bf16 v[116:119], v[216:219], v[176:179], v[116:119]
	ds_read_b128 v[232:235], v174 offset:12288
	v_mfma_f32_16x16x32_bf16 v[112:115], v[220:223], v[176:179], v[112:115]
	ds_read_b128 v[236:239], v174 offset:14336
	v_mfma_f32_16x16x32_bf16 v[92:95], v[208:211], v[180:183], v[92:95]
	v_mfma_f32_16x16x32_bf16 v[88:91], v[212:215], v[180:183], v[88:91]
	v_mfma_f32_16x16x32_bf16 v[84:87], v[216:219], v[180:183], v[84:87]
	v_mfma_f32_16x16x32_bf16 v[80:83], v[220:223], v[180:183], v[80:83]
	v_mfma_f32_16x16x32_bf16 v[60:63], v[208:211], v[184:187], v[60:63]
	v_mfma_f32_16x16x32_bf16 v[56:59], v[212:215], v[184:187], v[56:59]
	v_mfma_f32_16x16x32_bf16 v[52:55], v[216:219], v[184:187], v[52:55]
	v_mfma_f32_16x16x32_bf16 v[48:51], v[220:223], v[184:187], v[48:51]
	v_mfma_f32_16x16x32_bf16 v[28:31], v[208:211], v[188:191], v[28:31]
	v_mfma_f32_16x16x32_bf16 v[24:27], v[212:215], v[188:191], v[24:27]
	v_mfma_f32_16x16x32_bf16 v[20:23], v[216:219], v[188:191], v[20:23]
	v_mfma_f32_16x16x32_bf16 v[16:19], v[220:223], v[188:191], v[16:19]
	s_waitcnt lgkmcnt(0)
	v_mfma_f32_16x16x32_bf16 v[108:111], v[224:227], v[176:179], v[108:111]
	ds_read_b128 v[192:195], v173 offset:0
	v_mfma_f32_16x16x32_bf16 v[104:107], v[228:231], v[176:179], v[104:107]
	ds_read_b128 v[196:199], v173 offset:2048
	v_mfma_f32_16x16x32_bf16 v[100:103], v[232:235], v[176:179], v[100:103]
	ds_read_b128 v[200:203], v173 offset:4096
	v_mfma_f32_16x16x32_bf16 v[96:99], v[236:239], v[176:179], v[96:99]
	ds_read_b128 v[204:207], v173 offset:6144
	v_mfma_f32_16x16x32_bf16 v[76:79], v[224:227], v[180:183], v[76:79]
	ds_read_b128 v[208:211], v175 offset:0
	v_mfma_f32_16x16x32_bf16 v[72:75], v[228:231], v[180:183], v[72:75]
	ds_read_b128 v[212:215], v175 offset:2048
	v_mfma_f32_16x16x32_bf16 v[68:71], v[232:235], v[180:183], v[68:71]
	ds_read_b128 v[216:219], v175 offset:4096
	v_mfma_f32_16x16x32_bf16 v[64:67], v[236:239], v[180:183], v[64:67]
	ds_read_b128 v[220:223], v175 offset:6144
	v_mfma_f32_16x16x32_bf16 v[44:47], v[224:227], v[184:187], v[44:47]
	v_mfma_f32_16x16x32_bf16 v[40:43], v[228:231], v[184:187], v[40:43]
	v_mfma_f32_16x16x32_bf16 v[36:39], v[232:235], v[184:187], v[36:39]
	v_mfma_f32_16x16x32_bf16 v[32:35], v[236:239], v[184:187], v[32:35]
	v_mfma_f32_16x16x32_bf16 v[12:15], v[224:227], v[188:191], v[12:15]
	v_mfma_f32_16x16x32_bf16 v[8:11], v[228:231], v[188:191], v[8:11]
	v_mfma_f32_16x16x32_bf16 v[4:7], v[232:235], v[188:191], v[4:7]
	v_mfma_f32_16x16x32_bf16 v[0:3], v[236:239], v[188:191], v[0:3]
	s_waitcnt lgkmcnt(0)
	v_mfma_f32_16x16x32_bf16 v[124:127], v[208:211], v[192:195], v[124:127]
	ds_read_b128 v[224:227], v175 offset:8192
	v_mfma_f32_16x16x32_bf16 v[120:123], v[212:215], v[192:195], v[120:123]
	ds_read_b128 v[228:231], v175 offset:10240
	v_mfma_f32_16x16x32_bf16 v[116:119], v[216:219], v[192:195], v[116:119]
	ds_read_b128 v[232:235], v175 offset:12288
	v_mfma_f32_16x16x32_bf16 v[112:115], v[220:223], v[192:195], v[112:115]
	ds_read_b128 v[236:239], v175 offset:14336
	v_mfma_f32_16x16x32_bf16 v[92:95], v[208:211], v[196:199], v[92:95]
	v_mfma_f32_16x16x32_bf16 v[88:91], v[212:215], v[196:199], v[88:91]
	v_mfma_f32_16x16x32_bf16 v[84:87], v[216:219], v[196:199], v[84:87]
	v_mfma_f32_16x16x32_bf16 v[80:83], v[220:223], v[196:199], v[80:83]
	v_mfma_f32_16x16x32_bf16 v[60:63], v[208:211], v[200:203], v[60:63]
	v_mfma_f32_16x16x32_bf16 v[56:59], v[212:215], v[200:203], v[56:59]
	v_mfma_f32_16x16x32_bf16 v[52:55], v[216:219], v[200:203], v[52:55]
	v_mfma_f32_16x16x32_bf16 v[48:51], v[220:223], v[200:203], v[48:51]
	v_mfma_f32_16x16x32_bf16 v[28:31], v[208:211], v[204:207], v[28:31]
	v_mfma_f32_16x16x32_bf16 v[24:27], v[212:215], v[204:207], v[24:27]
	v_mfma_f32_16x16x32_bf16 v[20:23], v[216:219], v[204:207], v[20:23]
	v_mfma_f32_16x16x32_bf16 v[16:19], v[220:223], v[204:207], v[16:19]
	s_waitcnt lgkmcnt(0)
	s_waitcnt vmcnt(4)
	s_barrier
	s_mov_b32 s44, 2

.LBB0_1155:
	v_mov_b64_e32 v[0:1], v[132:133]
	v_mov_b64_e32 v[2:3], v[132:133]
	v_mov_b32_e32 v6, v154
	s_lshl_b32 s6, s76, 8
	v_lshl_add_u64 v[0:1], v[0:1], 0, s[22:23]
	v_ashrrev_i32_e32 v9, 3, v6
	v_add_u32_e32 v4, s6, v9
	v_lshrrev_b32_e32 v8, 4, v6
	v_ashrrev_i32_e32 v5, 31, v4
	v_xor_b32_e32 v10, v8, v6
	v_lshlrev_b64 v[4:5], 13, v[4:5]
	v_lshl_add_u64 v[0:1], v[0:1], 0, v[4:5]
	v_lshlrev_b32_e32 v4, 4, v10
	s_lshl_b32 s7, s3, 8
	v_and_b32_e32 v134, 0x70, v4
	v_lshl_add_u64 v[128:129], v[0:1], 0, v[134:135]
	v_add_u32_e32 v0, s7, v9
	v_ashrrev_i32_e32 v1, 31, v0
	v_lshl_add_u64 v[2:3], v[2:3], 0, s[16:17]
	v_lshlrev_b64 v[0:1], 13, v[0:1]
	v_ashrrev_i32_e32 v7, 6, v6
	v_lshl_add_u64 v[0:1], v[2:3], 0, v[0:1]
	v_lshl_add_u64 v[130:131], v[0:1], 0, v[134:135]
	v_ashrrev_i32_e32 v0, 1, v6
	v_and_b32_e32 v134, 0xffffffc0, v0
	v_lshlrev_b32_e32 v0, 7, v7
	v_and_b32_e32 v143, 0x80, v0
	v_lshlrev_b32_e32 v0, 10, v7
	v_add_u32_e32 v144, 0, v0
	v_add_u32_e32 v145, s79, v0
	v_readfirstlane_b32 s4, v144
	s_mov_b32 m0, s4
	v_readfirstlane_b32 s4, v145
	v_add_u32_e32 v146, 0x2000, v144
	global_load_lds_dwordx4 v[128:129], off
	s_mov_b32 m0, s4
	s_mov_b64 s[20:21], 0x80000
	v_readfirstlane_b32 s4, v146
	v_add_u32_e32 v147, 0x2000, v145
	global_load_lds_dwordx4 v[130:131], off
	v_lshl_add_u64 v[0:1], v[128:129], 0, s[20:21]
	s_mov_b32 m0, s4
	v_readfirstlane_b32 s4, v147
	v_add_u32_e32 v148, 0x4000, v144
	global_load_lds_dwordx4 v[0:1], off
	v_lshl_add_u64 v[0:1], v[130:131], 0, s[20:21]
	s_mov_b32 m0, s4
	s_mov_b64 s[20:21], 0x100000
	v_readfirstlane_b32 s4, v148
	v_add_u32_e32 v149, 0x4000, v145
	global_load_lds_dwordx4 v[0:1], off
	v_lshl_add_u64 v[0:1], v[128:129], 0, s[20:21]
	s_mov_b32 m0, s4
	v_readfirstlane_b32 s4, v149
	v_add_u32_e32 v151, 0x6000, v144
	global_load_lds_dwordx4 v[0:1], off
	v_lshl_add_u64 v[0:1], v[130:131], 0, s[20:21]
	s_mov_b32 m0, s4
	s_mov_b64 s[20:21], 0x180000
	v_readfirstlane_b32 s4, v151
	v_add_u32_e32 v152, 0x6000, v145
	global_load_lds_dwordx4 v[0:1], off
	v_lshl_add_u64 v[0:1], v[128:129], 0, s[20:21]
	s_mov_b32 m0, s4
	v_readfirstlane_b32 s4, v152
	global_load_lds_dwordx4 v[0:1], off
	v_lshl_add_u64 v[0:1], v[130:131], 0, s[20:21]
	s_mov_b32 m0, s4
	v_bfe_u32 v150, v6, 4, 2
	global_load_lds_dwordx4 v[0:1], off
	s_mov_b64 s[100:101], 0x80
	v_lshl_add_u64 v[240:241], v[128:129], 0, s[100:101]
	s_mov_b64 s[100:101], 0x80080
	v_lshl_add_u64 v[242:243], v[128:129], 0, s[100:101]
	s_mov_b64 s[100:101], 0x100080
	v_lshl_add_u64 v[244:245], v[128:129], 0, s[100:101]
	s_mov_b64 s[100:101], 0x180080
	v_lshl_add_u64 v[246:247], v[128:129], 0, s[100:101]
	s_mov_b64 s[100:101], 0x80
	v_lshl_add_u64 v[138:139], v[130:131], 0, s[100:101]
	s_mov_b64 s[100:101], 0x80080
	v_lshl_add_u64 v[140:141], v[130:131], 0, s[100:101]
	s_mov_b64 s[100:101], 0x100080
	v_lshl_add_u64 v[250:251], v[130:131], 0, s[100:101]
	s_mov_b64 s[100:101], 0x180080
	v_lshl_add_u64 v[252:253], v[130:131], 0, s[100:101]
	v_readfirstlane_b32 s100, v144
	v_readfirstlane_b32 s101, v145
	s_nop 3
	s_add_u32 m0, s100, 0x8000
	s_nop 0
	global_load_lds_dwordx4 v[240:241], off
	v_lshl_add_u64 v[240:241], v[240:241], 0, s[34:35]
	s_add_u32 m0, s100, 0xa000
	s_nop 0
	global_load_lds_dwordx4 v[242:243], off
	v_lshl_add_u64 v[242:243], v[242:243], 0, s[34:35]
	s_add_u32 m0, s100, 0xc000
	s_nop 0
	global_load_lds_dwordx4 v[244:245], off
	v_lshl_add_u64 v[244:245], v[244:245], 0, s[34:35]
	s_add_u32 m0, s100, 0xe000
	s_nop 0
	global_load_lds_dwordx4 v[246:247], off
	v_lshl_add_u64 v[246:247], v[246:247], 0, s[34:35]
	s_add_u32 m0, s101, 0x8000
	s_nop 0
	global_load_lds_dwordx4 v[138:139], off
	v_lshl_add_u64 v[138:139], v[138:139], 0, s[34:35]
	s_add_u32 m0, s101, 0xa000
	s_nop 0
	global_load_lds_dwordx4 v[140:141], off
	v_lshl_add_u64 v[140:141], v[140:141], 0, s[34:35]
	s_add_u32 m0, s101, 0xc000
	s_nop 0
	global_load_lds_dwordx4 v[250:251], off
	v_lshl_add_u64 v[250:251], v[250:251], 0, s[34:35]
	s_add_u32 m0, s101, 0xe000
	s_nop 0
	global_load_lds_dwordx4 v[252:253], off
	v_lshl_add_u64 v[252:253], v[252:253], 0, s[34:35]
	s_add_u32 m0, s100, 0x20000
	s_nop 0
	global_load_lds_dwordx4 v[240:241], off
	v_lshl_add_u64 v[240:241], v[240:241], 0, s[34:35]
	s_add_u32 m0, s100, 0x22000
	s_nop 0
	global_load_lds_dwordx4 v[242:243], off
	v_lshl_add_u64 v[242:243], v[242:243], 0, s[34:35]
	s_add_u32 m0, s100, 0x24000
	s_nop 0
	global_load_lds_dwordx4 v[244:245], off
	v_lshl_add_u64 v[244:245], v[244:245], 0, s[34:35]
	s_add_u32 m0, s100, 0x26000
	s_nop 0
	global_load_lds_dwordx4 v[246:247], off
	v_lshl_add_u64 v[246:247], v[246:247], 0, s[34:35]
	v_bfe_u32 v0, v6, 1, 3
	v_and_b32_e32 v142, 15, v6
	s_waitcnt vmcnt(12)
	v_bitop3_b32 v1, v8, v0, 3 bitop3:0x6c
	v_bitop3_b32 v0, v150, v0, 4 bitop3:0x36
	v_or_b32_e32 v2, v134, v142
	v_or_b32_e32 v3, v143, v142
	v_lshlrev_b32_e32 v171, 4, v0
	v_mov_b32_e32 v0, 0
	v_lshl_add_u32 v153, v2, 7, 0
	v_lshl_add_u32 v169, v3, 7, s79
	v_lshlrev_b32_e32 v170, 4, v1
	s_mov_b64 s[4:5], 0
	v_mov_b32_e32 v1, v0
	v_mov_b32_e32 v2, v0
	v_mov_b32_e32 v3, v0
	v_mov_b32_e32 v4, v0
	v_mov_b32_e32 v5, v0
	v_mov_b32_e32 v6, v0
	v_mov_b32_e32 v7, v0
	v_mov_b32_e32 v8, v0
	v_mov_b32_e32 v9, v0
	v_mov_b32_e32 v10, v0
	v_mov_b32_e32 v11, v0
	v_mov_b32_e32 v12, v0
	v_mov_b32_e32 v13, v0
	v_mov_b32_e32 v14, v0
	v_mov_b32_e32 v15, v0
	v_mov_b32_e32 v16, v0
	v_mov_b32_e32 v17, v0
	v_mov_b32_e32 v18, v0
	v_mov_b32_e32 v19, v0
	v_mov_b32_e32 v20, v0
	v_mov_b32_e32 v21, v0
	v_mov_b32_e32 v22, v0
	v_mov_b32_e32 v23, v0
	v_mov_b32_e32 v24, v0
	v_mov_b32_e32 v25, v0
	v_mov_b32_e32 v26, v0
	v_mov_b32_e32 v27, v0
	v_mov_b32_e32 v28, v0
	v_mov_b32_e32 v29, v0
	v_mov_b32_e32 v30, v0
	v_mov_b32_e32 v31, v0
	v_mov_b32_e32 v32, v0
	v_mov_b32_e32 v33, v0
	v_mov_b32_e32 v34, v0
	v_mov_b32_e32 v35, v0
	v_mov_b32_e32 v36, v0
	v_mov_b32_e32 v37, v0
	v_mov_b32_e32 v38, v0
	v_mov_b32_e32 v39, v0
	v_mov_b32_e32 v40, v0
	v_mov_b32_e32 v41, v0
	v_mov_b32_e32 v42, v0
	v_mov_b32_e32 v43, v0
	v_mov_b32_e32 v44, v0
	v_mov_b32_e32 v45, v0
	v_mov_b32_e32 v46, v0
	v_mov_b32_e32 v47, v0
	v_mov_b32_e32 v48, v0
	v_mov_b32_e32 v49, v0
	v_mov_b32_e32 v50, v0
	v_mov_b32_e32 v51, v0
	v_mov_b32_e32 v52, v0
	v_mov_b32_e32 v53, v0
	v_mov_b32_e32 v54, v0
	v_mov_b32_e32 v55, v0
	v_mov_b32_e32 v56, v0
	v_mov_b32_e32 v57, v0
	v_mov_b32_e32 v58, v0
	v_mov_b32_e32 v59, v0
	v_mov_b32_e32 v60, v0
	v_mov_b32_e32 v61, v0
	v_mov_b32_e32 v62, v0
	v_mov_b32_e32 v63, v0
	v_mov_b32_e32 v64, v0
	v_mov_b32_e32 v65, v0
	v_mov_b32_e32 v66, v0
	v_mov_b32_e32 v67, v0
	v_mov_b32_e32 v68, v0
	v_mov_b32_e32 v69, v0
	v_mov_b32_e32 v70, v0
	v_mov_b32_e32 v71, v0
	v_mov_b32_e32 v72, v0
	v_mov_b32_e32 v73, v0
	v_mov_b32_e32 v74, v0
	v_mov_b32_e32 v75, v0
	v_mov_b32_e32 v76, v0
	v_mov_b32_e32 v77, v0
	v_mov_b32_e32 v78, v0
	v_mov_b32_e32 v79, v0
	v_mov_b32_e32 v80, v0
	v_mov_b32_e32 v81, v0
	v_mov_b32_e32 v82, v0
	v_mov_b32_e32 v83, v0
	v_mov_b32_e32 v84, v0
	v_mov_b32_e32 v85, v0
	v_mov_b32_e32 v86, v0
	v_mov_b32_e32 v87, v0
	v_mov_b32_e32 v88, v0
	v_mov_b32_e32 v89, v0
	v_mov_b32_e32 v90, v0
	v_mov_b32_e32 v91, v0
	v_mov_b32_e32 v92, v0
	v_mov_b32_e32 v93, v0
	v_mov_b32_e32 v94, v0
	v_mov_b32_e32 v95, v0
	v_mov_b32_e32 v96, v0
	v_mov_b32_e32 v97, v0
	v_mov_b32_e32 v98, v0
	v_mov_b32_e32 v99, v0
	v_mov_b32_e32 v100, v0
	v_mov_b32_e32 v101, v0
	v_mov_b32_e32 v102, v0
	v_mov_b32_e32 v103, v0
	v_mov_b32_e32 v104, v0
	v_mov_b32_e32 v105, v0
	v_mov_b32_e32 v106, v0
	v_mov_b32_e32 v107, v0
	v_mov_b32_e32 v108, v0
	v_mov_b32_e32 v109, v0
	v_mov_b32_e32 v110, v0
	v_mov_b32_e32 v111, v0
	v_mov_b32_e32 v112, v0
	v_mov_b32_e32 v113, v0
	v_mov_b32_e32 v114, v0
	v_mov_b32_e32 v115, v0
	v_mov_b32_e32 v116, v0
	v_mov_b32_e32 v117, v0
	v_mov_b32_e32 v118, v0
	v_mov_b32_e32 v119, v0
	v_mov_b32_e32 v120, v0
	v_mov_b32_e32 v121, v0
	v_mov_b32_e32 v122, v0
	v_mov_b32_e32 v123, v0
	v_mov_b32_e32 v124, v0
	v_mov_b32_e32 v125, v0
	v_mov_b32_e32 v126, v0
	v_mov_b32_e32 v127, v0
	s_waitcnt vmcnt(12) lgkmcnt(0)
	s_barrier
	s_branch .LBB0_1157
.LBB0_1157:
	v_add_u32_e32 v172, v153, v170
	v_add_u32_e32 v173, v153, v171
	v_add_u32_e32 v174, v169, v170
	v_add_u32_e32 v175, v169, v171
	v_add_u32_e32 v254, 0x20000, v172
	v_add_u32_e32 v255, 0x20000, v173
	s_nop 1
	ds_read_b128 v[176:179], v172 offset:0
	ds_read_b128 v[180:183], v172 offset:2048
	ds_read_b128 v[184:187], v172 offset:4096
	ds_read_b128 v[188:191], v172 offset:6144
	ds_read_b128 v[208:211], v174 offset:0
	ds_read_b128 v[212:215], v174 offset:2048
	ds_read_b128 v[216:219], v174 offset:4096
	ds_read_b128 v[220:223], v174 offset:6144
	s_waitcnt lgkmcnt(0)
	v_mfma_f32_16x16x32_bf16 v[124:127], v[208:211], v[176:179], v[124:127]
	ds_read_b128 v[224:227], v174 offset:8192
	v_mfma_f32_16x16x32_bf16 v[120:123], v[212:215], v[176:179], v[120:123]
	ds_read_b128 v[228:231], v174 offset:10240
	v_mfma_f32_16x16x32_bf16 v[116:119], v[216:219], v[176:179], v[116:119]
	ds_read_b128 v[232:235], v174 offset:12288
	v_mfma_f32_16x16x32_bf16 v[112:115], v[220:223], v[176:179], v[112:115]
	ds_read_b128 v[236:239], v174 offset:14336
	v_mfma_f32_16x16x32_bf16 v[92:95], v[208:211], v[180:183], v[92:95]
	v_mfma_f32_16x16x32_bf16 v[88:91], v[212:215], v[180:183], v[88:91]
	v_mfma_f32_16x16x32_bf16 v[84:87], v[216:219], v[180:183], v[84:87]
	v_mfma_f32_16x16x32_bf16 v[80:83], v[220:223], v[180:183], v[80:83]
	v_mfma_f32_16x16x32_bf16 v[60:63], v[208:211], v[184:187], v[60:63]
	v_mfma_f32_16x16x32_bf16 v[56:59], v[212:215], v[184:187], v[56:59]
	v_mfma_f32_16x16x32_bf16 v[52:55], v[216:219], v[184:187], v[52:55]
	v_mfma_f32_16x16x32_bf16 v[48:51], v[220:223], v[184:187], v[48:51]
	v_mfma_f32_16x16x32_bf16 v[28:31], v[208:211], v[188:191], v[28:31]
	v_mfma_f32_16x16x32_bf16 v[24:27], v[212:215], v[188:191], v[24:27]
	v_mfma_f32_16x16x32_bf16 v[20:23], v[216:219], v[188:191], v[20:23]
	v_mfma_f32_16x16x32_bf16 v[16:19], v[220:223], v[188:191], v[16:19]
	s_waitcnt lgkmcnt(0)
	v_mfma_f32_16x16x32_bf16 v[108:111], v[224:227], v[176:179], v[108:111]
	ds_read_b128 v[192:195], v173 offset:0
	v_mfma_f32_16x16x32_bf16 v[104:107], v[228:231], v[176:179], v[104:107]
	ds_read_b128 v[196:199], v173 offset:2048
	v_mfma_f32_16x16x32_bf16 v[100:103], v[232:235], v[176:179], v[100:103]
	ds_read_b128 v[200:203], v173 offset:4096
	v_mfma_f32_16x16x32_bf16 v[96:99], v[236:239], v[176:179], v[96:99]
	ds_read_b128 v[204:207], v173 offset:6144
	v_mfma_f32_16x16x32_bf16 v[76:79], v[224:227], v[180:183], v[76:79]
	ds_read_b128 v[208:211], v175 offset:0
	v_mfma_f32_16x16x32_bf16 v[72:75], v[228:231], v[180:183], v[72:75]
	ds_read_b128 v[212:215], v175 offset:2048
	v_mfma_f32_16x16x32_bf16 v[68:71], v[232:235], v[180:183], v[68:71]
	ds_read_b128 v[216:219], v175 offset:4096
	v_mfma_f32_16x16x32_bf16 v[64:67], v[236:239], v[180:183], v[64:67]
	ds_read_b128 v[220:223], v175 offset:6144
	v_mfma_f32_16x16x32_bf16 v[44:47], v[224:227], v[184:187], v[44:47]
	v_mfma_f32_16x16x32_bf16 v[40:43], v[228:231], v[184:187], v[40:43]
	v_mfma_f32_16x16x32_bf16 v[36:39], v[232:235], v[184:187], v[36:39]
	v_mfma_f32_16x16x32_bf16 v[32:35], v[236:239], v[184:187], v[32:35]
	v_mfma_f32_16x16x32_bf16 v[12:15], v[224:227], v[188:191], v[12:15]
	v_mfma_f32_16x16x32_bf16 v[8:11], v[228:231], v[188:191], v[8:11]
	v_mfma_f32_16x16x32_bf16 v[4:7], v[232:235], v[188:191], v[4:7]
	v_mfma_f32_16x16x32_bf16 v[0:3], v[236:239], v[188:191], v[0:3]
	s_waitcnt lgkmcnt(0)
	v_mfma_f32_16x16x32_bf16 v[124:127], v[208:211], v[192:195], v[124:127]
	ds_read_b128 v[224:227], v175 offset:8192
	v_mfma_f32_16x16x32_bf16 v[120:123], v[212:215], v[192:195], v[120:123]
	ds_read_b128 v[228:231], v175 offset:10240
	v_mfma_f32_16x16x32_bf16 v[116:119], v[216:219], v[192:195], v[116:119]
	ds_read_b128 v[232:235], v175 offset:12288
	v_mfma_f32_16x16x32_bf16 v[112:115], v[220:223], v[192:195], v[112:115]
	ds_read_b128 v[236:239], v175 offset:14336
	v_mfma_f32_16x16x32_bf16 v[92:95], v[208:211], v[196:199], v[92:95]
	v_mfma_f32_16x16x32_bf16 v[88:91], v[212:215], v[196:199], v[88:91]
	v_mfma_f32_16x16x32_bf16 v[84:87], v[216:219], v[196:199], v[84:87]
	v_mfma_f32_16x16x32_bf16 v[80:83], v[220:223], v[196:199], v[80:83]
	v_mfma_f32_16x16x32_bf16 v[60:63], v[208:211], v[200:203], v[60:63]
	v_mfma_f32_16x16x32_bf16 v[56:59], v[212:215], v[200:203], v[56:59]
	v_mfma_f32_16x16x32_bf16 v[52:55], v[216:219], v[200:203], v[52:55]
	v_mfma_f32_16x16x32_bf16 v[48:51], v[220:223], v[200:203], v[48:51]
	v_mfma_f32_16x16x32_bf16 v[28:31], v[208:211], v[204:207], v[28:31]
	v_mfma_f32_16x16x32_bf16 v[24:27], v[212:215], v[204:207], v[24:27]
	v_mfma_f32_16x16x32_bf16 v[20:23], v[216:219], v[204:207], v[20:23]
	v_mfma_f32_16x16x32_bf16 v[16:19], v[220:223], v[204:207], v[16:19]
	s_waitcnt lgkmcnt(0)
	s_waitcnt vmcnt(4)
	s_barrier
	s_mov_b32 s44, 10
